# G2/G4 last unit: the unused re-read loads of the final K iteration fetch the unit's last two K-tiles (cache-resident) instead of its first two
# baseline (speedup 1.0000x reference)
.LBB0_369:
	s_nop 0
	v_cndmask_b32_e64 v2, 0, 1, s[2:3]
	v_cmp_ne_u32_e64 s[38:39], 1, v2
	s_andn2_b64 vcc, exec, s[2:3]
	s_mov_b64 s[2:3], s[40:41]
	s_lshr_b32 s34, s50, 8
	s_addk_i32 s34, 0xff00
	s_add_u32 s2, s2, s34
	s_addc_u32 s3, s3, 0
	s_cbranch_vccnz .LBB0_371
	s_mul_i32 s2, s50, s73
	s_mul_hi_i32 s3, s50, s73
	s_add_u32 s2, s52, s2
	s_addc_u32 s3, s53, s3
.LBB0_371:
	s_and_b64 vcc, exec, s[38:39]
	s_mov_b64 s[46:47], s[42:43]
	s_lshr_b32 s34, s50, 8
	s_addk_i32 s34, 0xff00
	s_add_u32 s46, s46, s34
	s_addc_u32 s47, s47, 0
	s_cbranch_vccnz .LBB0_373
	s_mul_i32 s46, s50, s72
	s_mul_hi_i32 s34, s50, s72
	s_add_u32 s46, s21, s46
	s_addc_u32 s47, s26, s34
